# attention priority flips with the halves swapped (waves 4-7: MFMA 3 / softmax 1, waves 0-3: MFMA 2 / softmax 0)
# baseline (speedup 1.0000x reference)
.LBB0_340:
	v_cmp_gt_u32_e32 vcc, 0x100, v206
	s_setprio 3
	s_cbranch_vccz .Lprio_2
	s_setprio 2
.Lprio_2:
	v_add_u32_e32 v101, s4, v96
	v_add_u32_e32 v100, s4, v95
	v_add_u32_e32 v99, s4, v94
	v_add_u32_e32 v98, s4, v93
	ds_read_b128 v[196:199], v101
	ds_read_b128 v[200:203], v100
	ds_read_b128 v[232:235], v101 offset:4096
	ds_read_b128 v[236:239], v100 offset:4096
	ds_read_b128 v[240:243], v99
	s_waitcnt lgkmcnt(4)
	v_mfma_f32_32x32x16_bf16 v[34:49], v[196:199], v[66:69], 0
	ds_read_b128 v[244:247], v99 offset:4096
	s_waitcnt lgkmcnt(4)
	v_mfma_f32_32x32x16_bf16 v[34:49], v[200:203], v[70:73], v[34:49]
	ds_read_b128 v[196:199], v98 offset:4096
	s_waitcnt lgkmcnt(4)
	v_mfma_f32_32x32x16_bf16 v[50:65], v[232:235], v[66:69], 0
	ds_read_b128 v[200:203], v98
	s_waitcnt lgkmcnt(4)
	v_mfma_f32_32x32x16_bf16 v[50:65], v[236:239], v[70:73], v[50:65]
	s_waitcnt lgkmcnt(3)
	v_mfma_f32_32x32x16_bf16 v[34:49], v[240:243], v[74:77], v[34:49]
	s_waitcnt lgkmcnt(2)
	v_mfma_f32_32x32x16_bf16 v[50:65], v[244:247], v[74:77], v[50:65]
	s_waitcnt lgkmcnt(1)
	v_mfma_f32_32x32x16_bf16 v[50:65], v[196:199], v[78:81], v[50:65]
	s_waitcnt lgkmcnt(0)
	v_mfma_f32_32x32x16_bf16 v[34:49], v[200:203], v[78:81], v[34:49]
	v_cmp_gt_u32_e32 vcc, 0x100, v206
	s_setprio 1
	s_cbranch_vccz .Lprio_1
	s_setprio 0

.Lprio_5:
	s_mul_i32 s0, s5, 0xa000
	v_add_u32_e32 v185, s0, v176
	v_add_u32_e32 v187, s0, v178
	v_add_u32_e32 v192, s0, v180
	v_add_u32_e32 v193, s0, v182
	ds_read_b128 v[196:199], v185
	ds_read_b128 v[200:203], v187
	ds_read_b128 v[232:235], v185 offset:12288
	ds_read_b128 v[236:239], v187 offset:12288
	ds_read_b128 v[240:243], v192
	s_waitcnt lgkmcnt(4)
	v_mfma_f32_32x32x16_bf16 v[66:81], v[196:199], v[98:101], 0
	ds_read_b128 v[244:247], v192 offset:12288
	s_waitcnt lgkmcnt(4)
	v_mfma_f32_32x32x16_bf16 v[66:81], v[200:203], v[102:105], v[66:81]
	ds_read_b128 v[196:199], v193
	s_waitcnt lgkmcnt(4)
	v_mfma_f32_32x32x16_bf16 v[82:97], v[232:235], v[98:101], 0
	ds_read_b128 v[200:203], v193 offset:12288
	s_waitcnt lgkmcnt(4)
	v_mfma_f32_32x32x16_bf16 v[82:97], v[236:239], v[102:105], v[82:97]
	ds_read_b128 v[232:235], v185 offset:128
	s_waitcnt lgkmcnt(4)
	v_mfma_f32_32x32x16_bf16 v[66:81], v[240:243], v[106:109], v[66:81]
	ds_read_b128 v[236:239], v185 offset:12416
	s_waitcnt lgkmcnt(4)
	v_mfma_f32_32x32x16_bf16 v[82:97], v[244:247], v[106:109], v[82:97]
	ds_read_b128 v[240:243], v187 offset:128
	s_waitcnt lgkmcnt(4)
	v_mfma_f32_32x32x16_bf16 v[66:81], v[196:199], v[110:113], v[66:81]
	ds_read_b128 v[244:247], v187 offset:12416
	s_waitcnt lgkmcnt(4)
	v_mfma_f32_32x32x16_bf16 v[82:97], v[200:203], v[110:113], v[82:97]
	ds_read_b128 v[196:199], v192 offset:128
	s_waitcnt lgkmcnt(4)
	v_mfma_f32_32x32x16_bf16 v[66:81], v[232:235], v[114:117], v[66:81]
	ds_read_b128 v[200:203], v192 offset:12416
	s_waitcnt lgkmcnt(4)
	v_mfma_f32_32x32x16_bf16 v[82:97], v[236:239], v[114:117], v[82:97]
	ds_read_b128 v[232:235], v193 offset:128
	s_waitcnt lgkmcnt(4)
	v_mfma_f32_32x32x16_bf16 v[66:81], v[240:243], v[118:121], v[66:81]
	ds_read_b128 v[236:239], v193 offset:12416
	s_waitcnt lgkmcnt(4)
	v_mfma_f32_32x32x16_bf16 v[82:97], v[244:247], v[118:121], v[82:97]
	ds_read_b128 v[240:243], v185 offset:256
	s_waitcnt lgkmcnt(4)
	v_mfma_f32_32x32x16_bf16 v[66:81], v[196:199], v[122:125], v[66:81]
	ds_read_b128 v[244:247], v185 offset:12544
	s_waitcnt lgkmcnt(4)
	v_mfma_f32_32x32x16_bf16 v[82:97], v[200:203], v[122:125], v[82:97]
	ds_read_b128 v[196:199], v187 offset:256
	s_waitcnt lgkmcnt(4)
	v_mfma_f32_32x32x16_bf16 v[66:81], v[232:235], v[126:129], v[66:81]
	ds_read_b128 v[200:203], v187 offset:12544
	s_waitcnt lgkmcnt(4)
	v_mfma_f32_32x32x16_bf16 v[82:97], v[236:239], v[126:129], v[82:97]
	ds_read_b128 v[232:235], v192 offset:256
	s_waitcnt lgkmcnt(4)
	v_mfma_f32_32x32x16_bf16 v[66:81], v[240:243], v[130:133], v[66:81]
	ds_read_b128 v[236:239], v192 offset:12544
	s_waitcnt lgkmcnt(4)
	v_mfma_f32_32x32x16_bf16 v[82:97], v[244:247], v[130:133], v[82:97]
	ds_read_b128 v[240:243], v193 offset:12544
	s_waitcnt lgkmcnt(4)
	v_mfma_f32_32x32x16_bf16 v[66:81], v[196:199], v[134:137], v[66:81]
	ds_read_b128 v[244:247], v193 offset:256
	s_waitcnt lgkmcnt(4)
	v_mfma_f32_32x32x16_bf16 v[82:97], v[200:203], v[134:137], v[82:97]
	s_waitcnt lgkmcnt(3)
	v_mfma_f32_32x32x16_bf16 v[66:81], v[232:235], v[138:141], v[66:81]
	s_waitcnt lgkmcnt(2)
	v_mfma_f32_32x32x16_bf16 v[82:97], v[236:239], v[138:141], v[82:97]
	s_waitcnt lgkmcnt(1)
	v_mfma_f32_32x32x16_bf16 v[82:97], v[240:243], v[142:145], v[82:97]
	s_waitcnt lgkmcnt(0)
	v_mfma_f32_32x32x16_bf16 v[66:81], v[244:247], v[142:145], v[66:81]
	v_cmp_gt_u32_e32 vcc, 0x100, v206
	s_setprio 1
	s_cbranch_vccz .Lprio_4
	s_setprio 0

.Lprio_8:
	v_add_u32_e32 v99, s4, v94
	v_add_u32_e32 v98, s4, v93
	v_add_u32_e32 v97, s4, v92
	v_add_u32_e32 v95, s4, v91
	ds_read_b128 v[196:199], v99
	ds_read_b128 v[200:203], v98
	ds_read_b128 v[232:235], v99 offset:4096
	ds_read_b128 v[236:239], v98 offset:4096
	ds_read_b128 v[240:243], v97
	s_waitcnt lgkmcnt(4)
	v_mfma_f32_32x32x16_bf16 v[34:49], v[196:199], v[66:69], 0
	ds_read_b128 v[244:247], v97 offset:4096
	s_waitcnt lgkmcnt(4)
	v_mfma_f32_32x32x16_bf16 v[34:49], v[200:203], v[70:73], v[34:49]
	ds_read_b128 v[196:199], v95 offset:4096
	s_waitcnt lgkmcnt(4)
	v_mfma_f32_32x32x16_bf16 v[50:65], v[232:235], v[66:69], 0
	ds_read_b128 v[200:203], v95
	s_waitcnt lgkmcnt(4)
	v_mfma_f32_32x32x16_bf16 v[50:65], v[236:239], v[70:73], v[50:65]
	s_waitcnt lgkmcnt(3)
	v_mfma_f32_32x32x16_bf16 v[34:49], v[240:243], v[74:77], v[34:49]
	s_waitcnt lgkmcnt(2)
	v_mfma_f32_32x32x16_bf16 v[50:65], v[244:247], v[74:77], v[50:65]
	s_waitcnt lgkmcnt(1)
	v_mfma_f32_32x32x16_bf16 v[50:65], v[196:199], v[78:81], v[50:65]
	s_waitcnt lgkmcnt(0)
	v_mfma_f32_32x32x16_bf16 v[34:49], v[200:203], v[78:81], v[34:49]
	v_cmp_gt_u32_e32 vcc, 0x100, v206
	s_setprio 1
	s_cbranch_vccz .Lprio_7
	s_setprio 0

.LBB0_400:
	s_andn2_b64 vcc, exec, s[4:5]
	s_cbranch_vccnz .LBB0_408
	v_cmp_gt_u32_e32 vcc, 0x100, v206
	s_setprio 3
	s_cbranch_vccz .Lprio_14
	s_setprio 2

.LBB0_405:
	v_cmp_gt_u32_e32 vcc, 0x100, v206
	s_setprio 1
	s_cbranch_vccz .Lprio_13
	s_setprio 0

.Lprio_11:
	s_mul_i32 s0, s12, 0xa000
	v_add_u32_e32 v187, s0, v178
	v_add_u32_e32 v189, s0, v180
	v_add_u32_e32 v194, s0, v182
	v_add_u32_e32 v195, s0, v184
	ds_read_b128 v[196:199], v187
	ds_read_b128 v[200:203], v189
	ds_read_b128 v[232:235], v187 offset:12288
	ds_read_b128 v[236:239], v189 offset:12288
	ds_read_b128 v[240:243], v194
	s_waitcnt lgkmcnt(4)
	v_mfma_f32_32x32x16_bf16 v[66:81], v[196:199], v[98:101], 0
	ds_read_b128 v[244:247], v194 offset:12288
	s_waitcnt lgkmcnt(4)
	v_mfma_f32_32x32x16_bf16 v[66:81], v[200:203], v[102:105], v[66:81]
	ds_read_b128 v[196:199], v195
	s_waitcnt lgkmcnt(4)
	v_mfma_f32_32x32x16_bf16 v[82:97], v[232:235], v[98:101], 0
	ds_read_b128 v[200:203], v195 offset:12288
	s_waitcnt lgkmcnt(4)
	v_mfma_f32_32x32x16_bf16 v[82:97], v[236:239], v[102:105], v[82:97]
	ds_read_b128 v[232:235], v187 offset:128
	s_waitcnt lgkmcnt(4)
	v_mfma_f32_32x32x16_bf16 v[66:81], v[240:243], v[106:109], v[66:81]
	ds_read_b128 v[236:239], v187 offset:12416
	s_waitcnt lgkmcnt(4)
	v_mfma_f32_32x32x16_bf16 v[82:97], v[244:247], v[106:109], v[82:97]
	ds_read_b128 v[240:243], v189 offset:128
	s_waitcnt lgkmcnt(4)
	v_mfma_f32_32x32x16_bf16 v[66:81], v[196:199], v[110:113], v[66:81]
	ds_read_b128 v[244:247], v189 offset:12416
	s_waitcnt lgkmcnt(4)
	v_mfma_f32_32x32x16_bf16 v[82:97], v[200:203], v[110:113], v[82:97]
	ds_read_b128 v[196:199], v194 offset:128
	s_waitcnt lgkmcnt(4)
	v_mfma_f32_32x32x16_bf16 v[66:81], v[232:235], v[114:117], v[66:81]
	ds_read_b128 v[200:203], v194 offset:12416
	s_waitcnt lgkmcnt(4)
	v_mfma_f32_32x32x16_bf16 v[82:97], v[236:239], v[114:117], v[82:97]
	ds_read_b128 v[232:235], v195 offset:128
	s_waitcnt lgkmcnt(4)
	v_mfma_f32_32x32x16_bf16 v[66:81], v[240:243], v[118:121], v[66:81]
	ds_read_b128 v[236:239], v195 offset:12416
	s_waitcnt lgkmcnt(4)
	v_mfma_f32_32x32x16_bf16 v[82:97], v[244:247], v[118:121], v[82:97]
	ds_read_b128 v[240:243], v187 offset:256
	s_waitcnt lgkmcnt(4)
	v_mfma_f32_32x32x16_bf16 v[66:81], v[196:199], v[122:125], v[66:81]
	ds_read_b128 v[244:247], v187 offset:12544
	s_waitcnt lgkmcnt(4)
	v_mfma_f32_32x32x16_bf16 v[82:97], v[200:203], v[122:125], v[82:97]
	ds_read_b128 v[196:199], v189 offset:256
	s_waitcnt lgkmcnt(4)
	v_mfma_f32_32x32x16_bf16 v[66:81], v[232:235], v[126:129], v[66:81]
	ds_read_b128 v[200:203], v189 offset:12544
	s_waitcnt lgkmcnt(4)
	v_mfma_f32_32x32x16_bf16 v[82:97], v[236:239], v[126:129], v[82:97]
	ds_read_b128 v[232:235], v194 offset:256
	s_waitcnt lgkmcnt(4)
	v_mfma_f32_32x32x16_bf16 v[66:81], v[240:243], v[130:133], v[66:81]
	ds_read_b128 v[236:239], v194 offset:12544
	s_waitcnt lgkmcnt(4)
	v_mfma_f32_32x32x16_bf16 v[82:97], v[244:247], v[130:133], v[82:97]
	ds_read_b128 v[240:243], v195 offset:12544
	s_waitcnt lgkmcnt(4)
	v_mfma_f32_32x32x16_bf16 v[66:81], v[196:199], v[134:137], v[66:81]
	ds_read_b128 v[244:247], v195 offset:256
	s_waitcnt lgkmcnt(4)
	v_mfma_f32_32x32x16_bf16 v[82:97], v[200:203], v[134:137], v[82:97]
	s_waitcnt lgkmcnt(3)
	v_mfma_f32_32x32x16_bf16 v[66:81], v[232:235], v[138:141], v[66:81]
	s_waitcnt lgkmcnt(2)
	v_mfma_f32_32x32x16_bf16 v[82:97], v[236:239], v[138:141], v[82:97]
	s_waitcnt lgkmcnt(1)
	v_mfma_f32_32x32x16_bf16 v[82:97], v[240:243], v[142:145], v[82:97]
	s_waitcnt lgkmcnt(0)
	v_mfma_f32_32x32x16_bf16 v[66:81], v[244:247], v[142:145], v[66:81]
	v_cmp_gt_u32_e32 vcc, 0x100, v206
	s_setprio 1
	s_cbranch_vccz .Lprio_10
	s_setprio 0
